# P4 LayerNorm gamma/beta loads issued before the statistics exchange wait instead of after it
# baseline (speedup 1.0000x reference)
.LBB0_412:
	s_or_b64 exec, exec, s[46:47]
	v_lshlrev_b64 v[246:247], 2, v[128:129]
	v_lshl_add_u64 v[248:249], s[54:55], 0, v[246:247]
	v_lshl_add_u64 v[246:247], s[56:57], 0, v[246:247]
	global_load_dwordx4 v[210:213], v[246:247], off
	global_load_dwordx4 v[214:217], v[248:249], off
	global_load_dwordx4 v[218:221], v[248:249], off offset:64
	global_load_dwordx4 v[222:225], v[246:247], off offset:64
	global_load_dwordx4 v[226:229], v[246:247], off offset:512
	global_load_dwordx4 v[230:233], v[248:249], off offset:512
	global_load_dwordx4 v[234:237], v[248:249], off offset:576
	global_load_dwordx4 v[238:241], v[246:247], off offset:576
	s_andn2_b64 vcc, exec, s[30:31]
	s_cbranch_vccnz .LBB0_429
	s_memrealtime s[46:47]
	s_lshl_b32 s48, s14, 6
	s_ashr_i32 s49, s48, 31
	s_lshl_b64 s[48:49], s[48:49], 2
	s_add_u32 s48, s64, s48
	s_addc_u32 s49, s65, s49
	s_branch .LBB0_416

.LBB0_431:
	s_or_b64 exec, exec, s[46:47]
	v_lshlrev_b64 v[178:179], 2, v[128:129]
	s_waitcnt lgkmcnt(0)
	s_barrier
	v_lshl_add_u64 v[128:129], s[54:55], 0, v[178:179]
	v_lshl_add_u64 v[132:133], s[56:57], 0, v[178:179]
	v_mov_b32_e32 v152, v210
	v_mov_b32_e32 v153, v211
	v_mov_b32_e32 v154, v212
	v_mov_b32_e32 v155, v213
	v_mov_b32_e32 v156, v214
	v_mov_b32_e32 v157, v215
	v_mov_b32_e32 v158, v216
	v_mov_b32_e32 v159, v217
	v_mov_b32_e32 v144, v218
	v_mov_b32_e32 v145, v219
	v_mov_b32_e32 v146, v220
	v_mov_b32_e32 v147, v221
	v_mov_b32_e32 v148, v222
	v_mov_b32_e32 v149, v223
	v_mov_b32_e32 v150, v224
	v_mov_b32_e32 v151, v225
	v_mov_b32_e32 v136, v226
	v_mov_b32_e32 v137, v227
	v_mov_b32_e32 v138, v228
	v_mov_b32_e32 v139, v229
	v_mov_b32_e32 v140, v230
	v_mov_b32_e32 v141, v231
	v_mov_b32_e32 v142, v232
	v_mov_b32_e32 v143, v233
	s_nop 0
	v_mov_b32_e32 v128, v234
	v_mov_b32_e32 v129, v235
	v_mov_b32_e32 v130, v236
	v_mov_b32_e32 v131, v237
	s_nop 0
	v_mov_b32_e32 v132, v238
	v_mov_b32_e32 v133, v239
	v_mov_b32_e32 v134, v240
	v_mov_b32_e32 v135, v241
	v_lshlrev_b64 v[176:177], 10, v[176:177]
	v_lshl_add_u64 v[212:213], v[176:177], 2, s[58:59]
	ds_read_b64 v[214:215], v192
	ds_read_b64 v[176:177], v193
	ds_read_b64 v[216:217], v194
	ds_read_b64 v[218:219], v195
	s_waitcnt lgkmcnt(4)
	v_cmp_ne_u32_e32 vcc, 0, v164
	s_waitcnt lgkmcnt(3)
	v_sub_f32_e32 v47, v47, v214
	v_sub_f32_e32 v46, v46, v214
	v_sub_f32_e32 v45, v45, v214
	v_sub_f32_e32 v44, v44, v214
	v_sub_f32_e32 v41, v41, v214
	v_sub_f32_e32 v40, v40, v214
	v_sub_f32_e32 v43, v43, v214
	v_sub_f32_e32 v42, v42, v214
	v_sub_f32_e32 v39, v39, v214
	v_sub_f32_e32 v38, v38, v214
	v_sub_f32_e32 v37, v37, v214
	v_sub_f32_e32 v36, v36, v214
	v_sub_f32_e32 v35, v35, v214
	v_sub_f32_e32 v34, v34, v214
	v_sub_f32_e32 v33, v33, v214
	v_sub_f32_e32 v32, v32, v214
	v_pk_mul_f32 v[44:45], v[214:215], v[44:45] op_sel:[1,0]
	v_pk_mul_f32 v[46:47], v[214:215], v[46:47] op_sel:[1,0]
	v_pk_mul_f32 v[40:41], v[214:215], v[40:41] op_sel:[1,0]
	v_add_u32_e32 v210, s39, v184
	v_pk_mul_f32 v[42:43], v[214:215], v[42:43] op_sel:[1,0]
	v_pk_mul_f32 v[36:37], v[214:215], v[36:37] op_sel:[1,0]
	v_pk_mul_f32 v[38:39], v[214:215], v[38:39] op_sel:[1,0]
	v_pk_mul_f32 v[32:33], v[214:215], v[32:33] op_sel:[1,0]
	v_pk_mul_f32 v[34:35], v[214:215], v[34:35] op_sel:[1,0]
	s_or_b64 vcc, vcc, s[0:1]
	s_mov_b64 s[84:85], vcc
	s_mov_b32 s86, 0x55555555
	s_mov_b32 s87, 0x55555555
	s_mov_b64 vcc, s[86:87]
	v_and_b32_e32 v238, 1, v203
	v_sub_u32_e32 v239, 0, v238
	v_and_b32_e32 v238, 0xfffff040, v239
	v_add_u32_e32 v240, 0x1000, v238
	v_mov_b32_e32 v241, 0
	v_ashrrev_i32_e32 v211, 31, v210
	v_lshl_add_u64 v[212:213], v[212:213], 0, v[178:179]
	s_waitcnt lgkmcnt(2)
	v_sub_f32_e32 v91, v91, v176
	v_sub_f32_e32 v90, v90, v176
	v_sub_f32_e32 v89, v89, v176
	v_sub_f32_e32 v88, v88, v176
	v_pk_mul_f32 v[88:89], v[176:177], v[88:89] op_sel:[1,0]
	v_pk_mul_f32 v[90:91], v[176:177], v[90:91] op_sel:[1,0]
	s_waitcnt vmcnt(6)
	v_pk_fma_f32 v[46:47], v[158:159], v[46:47], v[154:155]
	v_pk_fma_f32 v[44:45], v[156:157], v[44:45], v[152:153]
	s_waitcnt vmcnt(4)
	v_pk_fma_f32 v[40:41], v[144:145], v[40:41], v[148:149]
	v_pk_fma_f32 v[42:43], v[146:147], v[42:43], v[150:151]
	s_waitcnt vmcnt(2)
	v_pk_fma_f32 v[214:215], v[142:143], v[38:39], v[138:139]
	v_pk_fma_f32 v[220:221], v[140:141], v[36:37], v[136:137]
	s_waitcnt vmcnt(0)
	v_pk_fma_f32 v[222:223], v[130:131], v[34:35], v[134:135]
	v_pk_fma_f32 v[224:225], v[128:129], v[32:33], v[132:133]
	v_cndmask_b32_e64 v35, v47, v209, s[84:85]
	v_cndmask_b32_e64 v34, v46, v209, s[84:85]
	v_cndmask_b32_e64 v33, v45, v209, s[84:85]
	v_cndmask_b32_e64 v32, v44, v209, s[84:85]
	v_cndmask_b32_e64 v37, v41, v209, s[84:85]
	v_cndmask_b32_e64 v36, v40, v209, s[84:85]
	v_cndmask_b32_e64 v39, v43, v209, s[84:85]
	v_cndmask_b32_e64 v38, v42, v209, s[84:85]
	v_cndmask_b32_e64 v43, v215, v209, s[84:85]
	v_cndmask_b32_e64 v42, v214, v209, s[84:85]
	v_cndmask_b32_e64 v41, v221, v209, s[84:85]
	v_cndmask_b32_e64 v40, v220, v209, s[84:85]
	v_cndmask_b32_e64 v47, v223, v209, s[84:85]
	v_cndmask_b32_e64 v46, v222, v209, s[84:85]
	v_cndmask_b32_e64 v45, v225, v209, s[84:85]
	v_cndmask_b32_e64 v44, v224, v209, s[84:85]
	v_mov_b32_e32 v226, v32
	v_mov_b32_e32 v227, v33
	v_mov_b32_e32 v228, v34
	v_mov_b32_e32 v229, v35
	s_nop 1
	v_cndmask_b32_dpp v234, v36, v226, vcc quad_perm:[1,0,3,2] row_mask:0xf bank_mask:0xf
	v_cndmask_b32_dpp v235, v37, v227, vcc quad_perm:[1,0,3,2] row_mask:0xf bank_mask:0xf
	v_cndmask_b32_dpp v236, v38, v228, vcc quad_perm:[1,0,3,2] row_mask:0xf bank_mask:0xf
	v_cndmask_b32_dpp v237, v39, v229, vcc quad_perm:[1,0,3,2] row_mask:0xf bank_mask:0xf
	s_not_b64 vcc, vcc
	s_nop 0
	v_cndmask_b32_dpp v36, v226, v36, vcc quad_perm:[1,0,3,2] row_mask:0xf bank_mask:0xf
	v_cndmask_b32_dpp v37, v227, v37, vcc quad_perm:[1,0,3,2] row_mask:0xf bank_mask:0xf
	v_cndmask_b32_dpp v38, v228, v38, vcc quad_perm:[1,0,3,2] row_mask:0xf bank_mask:0xf
	v_cndmask_b32_dpp v39, v229, v39, vcc quad_perm:[1,0,3,2] row_mask:0xf bank_mask:0xf
	s_not_b64 vcc, vcc
	v_lshl_add_u64 v[242:243], v[212:213], 0, v[238:239]
	v_lshl_add_u64 v[244:245], v[212:213], 0, v[240:241]
	global_store_dwordx4 v[242:243], v[234:237], off
	global_store_dwordx4 v[244:245], v[36:39], off
	v_mov_b32_e32 v230, v40
	v_mov_b32_e32 v231, v41
	v_mov_b32_e32 v232, v42
	v_mov_b32_e32 v233, v43
	s_nop 1
	v_cndmask_b32_dpp v234, v44, v230, vcc quad_perm:[1,0,3,2] row_mask:0xf bank_mask:0xf
	v_cndmask_b32_dpp v235, v45, v231, vcc quad_perm:[1,0,3,2] row_mask:0xf bank_mask:0xf
	v_cndmask_b32_dpp v236, v46, v232, vcc quad_perm:[1,0,3,2] row_mask:0xf bank_mask:0xf
	v_cndmask_b32_dpp v237, v47, v233, vcc quad_perm:[1,0,3,2] row_mask:0xf bank_mask:0xf
	s_not_b64 vcc, vcc
	s_nop 0
	v_cndmask_b32_dpp v44, v230, v44, vcc quad_perm:[1,0,3,2] row_mask:0xf bank_mask:0xf
	v_cndmask_b32_dpp v45, v231, v45, vcc quad_perm:[1,0,3,2] row_mask:0xf bank_mask:0xf
	v_cndmask_b32_dpp v46, v232, v46, vcc quad_perm:[1,0,3,2] row_mask:0xf bank_mask:0xf
	v_cndmask_b32_dpp v47, v233, v47, vcc quad_perm:[1,0,3,2] row_mask:0xf bank_mask:0xf
	s_not_b64 vcc, vcc
	v_lshl_add_u64 v[242:243], v[212:213], 0, v[238:239]
	v_lshl_add_u64 v[244:245], v[212:213], 0, v[240:241]
	global_store_dwordx4 v[242:243], v[234:237], off offset:512
	global_store_dwordx4 v[244:245], v[44:47], off offset:512
	v_lshlrev_b64 v[36:37], 12, v[210:211]
	v_pk_fma_f32 v[90:91], v[158:159], v[90:91], v[154:155]
	v_pk_fma_f32 v[88:89], v[156:157], v[88:89], v[152:153]
	v_lshl_add_u64 v[36:37], s[58:59], 0, v[36:37]
	v_cndmask_b32_e64 v35, v91, v209, s[84:85]
	v_cndmask_b32_e64 v34, v90, v209, s[84:85]
	v_cndmask_b32_e64 v33, v89, v209, s[84:85]
	v_cndmask_b32_e64 v32, v88, v209, s[84:85]
	v_lshl_add_u64 v[36:37], v[36:37], 0, v[178:179]
	v_mov_b32_e32 v226, v32
	v_mov_b32_e32 v227, v33
	v_mov_b32_e32 v228, v34
	v_mov_b32_e32 v229, v35
	s_nop 1
	v_sub_f32_e32 v33, v59, v176
	v_sub_f32_e32 v32, v58, v176
	v_sub_f32_e32 v35, v57, v176
	v_sub_f32_e32 v34, v56, v176
	v_pk_mul_f32 v[34:35], v[176:177], v[34:35] op_sel:[1,0]
	v_pk_mul_f32 v[32:33], v[176:177], v[32:33] op_sel:[1,0]
	v_pk_fma_f32 v[38:39], v[144:145], v[34:35], v[148:149]
	v_pk_fma_f32 v[32:33], v[146:147], v[32:33], v[150:151]
	s_nop 0
	v_cndmask_b32_e64 v35, v33, v209, s[84:85]
	v_cndmask_b32_e64 v34, v32, v209, s[84:85]
	v_cndmask_b32_e64 v33, v39, v209, s[84:85]
	v_cndmask_b32_e64 v32, v38, v209, s[84:85]
	s_nop 1
	v_cndmask_b32_dpp v234, v32, v226, vcc quad_perm:[1,0,3,2] row_mask:0xf bank_mask:0xf
	v_cndmask_b32_dpp v235, v33, v227, vcc quad_perm:[1,0,3,2] row_mask:0xf bank_mask:0xf
	v_cndmask_b32_dpp v236, v34, v228, vcc quad_perm:[1,0,3,2] row_mask:0xf bank_mask:0xf
	v_cndmask_b32_dpp v237, v35, v229, vcc quad_perm:[1,0,3,2] row_mask:0xf bank_mask:0xf
	s_not_b64 vcc, vcc
	s_nop 0
	v_cndmask_b32_dpp v32, v226, v32, vcc quad_perm:[1,0,3,2] row_mask:0xf bank_mask:0xf
	v_cndmask_b32_dpp v33, v227, v33, vcc quad_perm:[1,0,3,2] row_mask:0xf bank_mask:0xf
	v_cndmask_b32_dpp v34, v228, v34, vcc quad_perm:[1,0,3,2] row_mask:0xf bank_mask:0xf
	v_cndmask_b32_dpp v35, v229, v35, vcc quad_perm:[1,0,3,2] row_mask:0xf bank_mask:0xf
	s_not_b64 vcc, vcc
	v_lshl_add_u64 v[242:243], v[36:37], 0, v[238:239]
	v_lshl_add_u64 v[244:245], v[36:37], 0, v[240:241]
	global_store_dwordx4 v[242:243], v[234:237], off
	global_store_dwordx4 v[244:245], v[32:35], off
	s_nop 1
	v_sub_f32_e32 v33, v55, v176
	v_sub_f32_e32 v32, v54, v176
	v_sub_f32_e32 v35, v53, v176
	v_sub_f32_e32 v34, v52, v176
	v_pk_mul_f32 v[34:35], v[176:177], v[34:35] op_sel:[1,0]
	v_pk_mul_f32 v[32:33], v[176:177], v[32:33] op_sel:[1,0]
	v_pk_fma_f32 v[38:39], v[140:141], v[34:35], v[136:137]
	v_pk_fma_f32 v[32:33], v[142:143], v[32:33], v[138:139]
	s_nop 0
	v_cndmask_b32_e64 v35, v33, v209, s[84:85]
	v_cndmask_b32_e64 v34, v32, v209, s[84:85]
	v_cndmask_b32_e64 v33, v39, v209, s[84:85]
	v_cndmask_b32_e64 v32, v38, v209, s[84:85]
	v_mov_b32_e32 v230, v32
	v_mov_b32_e32 v231, v33
	v_mov_b32_e32 v232, v34
	v_mov_b32_e32 v233, v35
	s_nop 1
	v_sub_f32_e32 v33, v51, v176
	v_sub_f32_e32 v32, v50, v176
	v_sub_f32_e32 v35, v49, v176
	v_sub_f32_e32 v34, v48, v176
	v_pk_mul_f32 v[34:35], v[176:177], v[34:35] op_sel:[1,0]
	v_pk_mul_f32 v[32:33], v[176:177], v[32:33] op_sel:[1,0]
	v_pk_fma_f32 v[38:39], v[128:129], v[34:35], v[132:133]
	v_pk_fma_f32 v[32:33], v[130:131], v[32:33], v[134:135]
	s_nop 0
	v_cndmask_b32_e64 v35, v33, v209, s[84:85]
	v_cndmask_b32_e64 v34, v32, v209, s[84:85]
	v_cndmask_b32_e64 v33, v39, v209, s[84:85]
	v_cndmask_b32_e64 v32, v38, v209, s[84:85]
	s_nop 1
	v_cndmask_b32_dpp v234, v32, v230, vcc quad_perm:[1,0,3,2] row_mask:0xf bank_mask:0xf
	v_cndmask_b32_dpp v235, v33, v231, vcc quad_perm:[1,0,3,2] row_mask:0xf bank_mask:0xf
	v_cndmask_b32_dpp v236, v34, v232, vcc quad_perm:[1,0,3,2] row_mask:0xf bank_mask:0xf
	v_cndmask_b32_dpp v237, v35, v233, vcc quad_perm:[1,0,3,2] row_mask:0xf bank_mask:0xf
	s_not_b64 vcc, vcc
	s_nop 0
	v_cndmask_b32_dpp v32, v230, v32, vcc quad_perm:[1,0,3,2] row_mask:0xf bank_mask:0xf
	v_cndmask_b32_dpp v33, v231, v33, vcc quad_perm:[1,0,3,2] row_mask:0xf bank_mask:0xf
	v_cndmask_b32_dpp v34, v232, v34, vcc quad_perm:[1,0,3,2] row_mask:0xf bank_mask:0xf
	v_cndmask_b32_dpp v35, v233, v35, vcc quad_perm:[1,0,3,2] row_mask:0xf bank_mask:0xf
	s_not_b64 vcc, vcc
	v_lshl_add_u64 v[242:243], v[36:37], 0, v[238:239]
	v_lshl_add_u64 v[244:245], v[36:37], 0, v[240:241]
	global_store_dwordx4 v[242:243], v[234:237], off offset:512
	global_store_dwordx4 v[244:245], v[32:35], off offset:512
	v_add_u32_e32 v36, s39, v185
	v_ashrrev_i32_e32 v37, 31, v36
	s_waitcnt lgkmcnt(1)
	v_sub_f32_e32 v33, v99, v216
	v_sub_f32_e32 v32, v98, v216
	v_sub_f32_e32 v35, v97, v216
	v_sub_f32_e32 v34, v96, v216
	v_pk_mul_f32 v[34:35], v[216:217], v[34:35] op_sel:[1,0]
	v_pk_mul_f32 v[32:33], v[216:217], v[32:33] op_sel:[1,0]
	v_lshlrev_b64 v[36:37], 12, v[36:37]
	v_pk_fma_f32 v[32:33], v[158:159], v[32:33], v[154:155]
	v_pk_fma_f32 v[38:39], v[156:157], v[34:35], v[152:153]
	v_lshl_add_u64 v[36:37], s[58:59], 0, v[36:37]
	v_cndmask_b32_e64 v35, v33, v209, s[84:85]
	v_cndmask_b32_e64 v34, v32, v209, s[84:85]
	v_cndmask_b32_e64 v33, v39, v209, s[84:85]
	v_cndmask_b32_e64 v32, v38, v209, s[84:85]
	v_lshl_add_u64 v[36:37], v[36:37], 0, v[178:179]
	v_mov_b32_e32 v226, v32
	v_mov_b32_e32 v227, v33
	v_mov_b32_e32 v228, v34
	v_mov_b32_e32 v229, v35
	s_nop 1
	v_sub_f32_e32 v33, v83, v216
	v_sub_f32_e32 v32, v82, v216
	v_sub_f32_e32 v35, v81, v216
	v_sub_f32_e32 v34, v80, v216
	v_pk_mul_f32 v[34:35], v[216:217], v[34:35] op_sel:[1,0]
	v_pk_mul_f32 v[32:33], v[216:217], v[32:33] op_sel:[1,0]
	v_pk_fma_f32 v[38:39], v[144:145], v[34:35], v[148:149]
	v_pk_fma_f32 v[32:33], v[146:147], v[32:33], v[150:151]
	s_nop 0
	v_cndmask_b32_e64 v35, v33, v209, s[84:85]
	v_cndmask_b32_e64 v34, v32, v209, s[84:85]
	v_cndmask_b32_e64 v33, v39, v209, s[84:85]
	v_cndmask_b32_e64 v32, v38, v209, s[84:85]
	s_nop 1
	v_cndmask_b32_dpp v234, v32, v226, vcc quad_perm:[1,0,3,2] row_mask:0xf bank_mask:0xf
	v_cndmask_b32_dpp v235, v33, v227, vcc quad_perm:[1,0,3,2] row_mask:0xf bank_mask:0xf
	v_cndmask_b32_dpp v236, v34, v228, vcc quad_perm:[1,0,3,2] row_mask:0xf bank_mask:0xf
	v_cndmask_b32_dpp v237, v35, v229, vcc quad_perm:[1,0,3,2] row_mask:0xf bank_mask:0xf
	s_not_b64 vcc, vcc
	s_nop 0
	v_cndmask_b32_dpp v32, v226, v32, vcc quad_perm:[1,0,3,2] row_mask:0xf bank_mask:0xf
	v_cndmask_b32_dpp v33, v227, v33, vcc quad_perm:[1,0,3,2] row_mask:0xf bank_mask:0xf
	v_cndmask_b32_dpp v34, v228, v34, vcc quad_perm:[1,0,3,2] row_mask:0xf bank_mask:0xf
	v_cndmask_b32_dpp v35, v229, v35, vcc quad_perm:[1,0,3,2] row_mask:0xf bank_mask:0xf
	s_not_b64 vcc, vcc
	v_lshl_add_u64 v[242:243], v[36:37], 0, v[238:239]
	v_lshl_add_u64 v[244:245], v[36:37], 0, v[240:241]
	global_store_dwordx4 v[242:243], v[234:237], off
	global_store_dwordx4 v[244:245], v[32:35], off
	s_nop 1
	v_sub_f32_e32 v33, v79, v216
	v_sub_f32_e32 v32, v78, v216
	v_sub_f32_e32 v35, v77, v216
	v_sub_f32_e32 v34, v76, v216
	v_pk_mul_f32 v[34:35], v[216:217], v[34:35] op_sel:[1,0]
	v_pk_mul_f32 v[32:33], v[216:217], v[32:33] op_sel:[1,0]
	v_pk_fma_f32 v[38:39], v[140:141], v[34:35], v[136:137]
	v_pk_fma_f32 v[32:33], v[142:143], v[32:33], v[138:139]
	s_nop 0
	v_cndmask_b32_e64 v35, v33, v209, s[84:85]
	v_cndmask_b32_e64 v34, v32, v209, s[84:85]
	v_cndmask_b32_e64 v33, v39, v209, s[84:85]
	v_cndmask_b32_e64 v32, v38, v209, s[84:85]
	v_mov_b32_e32 v230, v32
	v_mov_b32_e32 v231, v33
	v_mov_b32_e32 v232, v34
	v_mov_b32_e32 v233, v35
	s_nop 1
	v_sub_f32_e32 v33, v71, v216
	v_sub_f32_e32 v32, v70, v216
	v_sub_f32_e32 v35, v69, v216
	v_sub_f32_e32 v34, v68, v216
	v_pk_mul_f32 v[34:35], v[216:217], v[34:35] op_sel:[1,0]
	v_pk_mul_f32 v[32:33], v[216:217], v[32:33] op_sel:[1,0]
	v_pk_fma_f32 v[38:39], v[128:129], v[34:35], v[132:133]
	v_pk_fma_f32 v[32:33], v[130:131], v[32:33], v[134:135]
	s_nop 0
	v_cndmask_b32_e64 v35, v33, v209, s[84:85]
	v_cndmask_b32_e64 v34, v32, v209, s[84:85]
	v_cndmask_b32_e64 v33, v39, v209, s[84:85]
	v_cndmask_b32_e64 v32, v38, v209, s[84:85]
	s_nop 1
	v_cndmask_b32_dpp v234, v32, v230, vcc quad_perm:[1,0,3,2] row_mask:0xf bank_mask:0xf
	v_cndmask_b32_dpp v235, v33, v231, vcc quad_perm:[1,0,3,2] row_mask:0xf bank_mask:0xf
	v_cndmask_b32_dpp v236, v34, v232, vcc quad_perm:[1,0,3,2] row_mask:0xf bank_mask:0xf
	v_cndmask_b32_dpp v237, v35, v233, vcc quad_perm:[1,0,3,2] row_mask:0xf bank_mask:0xf
	s_not_b64 vcc, vcc
	s_nop 0
	v_cndmask_b32_dpp v32, v230, v32, vcc quad_perm:[1,0,3,2] row_mask:0xf bank_mask:0xf
	v_cndmask_b32_dpp v33, v231, v33, vcc quad_perm:[1,0,3,2] row_mask:0xf bank_mask:0xf
	v_cndmask_b32_dpp v34, v232, v34, vcc quad_perm:[1,0,3,2] row_mask:0xf bank_mask:0xf
	v_cndmask_b32_dpp v35, v233, v35, vcc quad_perm:[1,0,3,2] row_mask:0xf bank_mask:0xf
	s_not_b64 vcc, vcc
	v_lshl_add_u64 v[242:243], v[36:37], 0, v[238:239]
	v_lshl_add_u64 v[244:245], v[36:37], 0, v[240:241]
	global_store_dwordx4 v[242:243], v[234:237], off offset:512
	global_store_dwordx4 v[244:245], v[32:35], off offset:512
	v_add_u32_e32 v36, s39, v186
	v_ashrrev_i32_e32 v37, 31, v36
	s_waitcnt lgkmcnt(0)
	v_sub_f32_e32 v33, v123, v218
	v_sub_f32_e32 v32, v122, v218
	v_sub_f32_e32 v35, v121, v218
	v_sub_f32_e32 v34, v120, v218
	v_pk_mul_f32 v[34:35], v[218:219], v[34:35] op_sel:[1,0]
	v_pk_mul_f32 v[32:33], v[218:219], v[32:33] op_sel:[1,0]
	v_lshlrev_b64 v[36:37], 12, v[36:37]
	v_pk_fma_f32 v[32:33], v[158:159], v[32:33], v[154:155]
	v_pk_fma_f32 v[38:39], v[156:157], v[34:35], v[152:153]
	v_lshl_add_u64 v[36:37], s[58:59], 0, v[36:37]
	v_cndmask_b32_e64 v35, v33, v209, s[84:85]
	v_cndmask_b32_e64 v34, v32, v209, s[84:85]
	v_cndmask_b32_e64 v33, v39, v209, s[84:85]
	v_cndmask_b32_e64 v32, v38, v209, s[84:85]
	v_lshl_add_u64 v[36:37], v[36:37], 0, v[178:179]
	v_mov_b32_e32 v226, v32
	v_mov_b32_e32 v227, v33
	v_mov_b32_e32 v228, v34
	v_mov_b32_e32 v229, v35
	s_nop 1
	v_sub_f32_e32 v33, v115, v218
	v_sub_f32_e32 v32, v114, v218
	v_sub_f32_e32 v35, v113, v218
	v_sub_f32_e32 v34, v112, v218
	v_pk_mul_f32 v[34:35], v[218:219], v[34:35] op_sel:[1,0]
	v_pk_mul_f32 v[32:33], v[218:219], v[32:33] op_sel:[1,0]
	v_pk_fma_f32 v[38:39], v[144:145], v[34:35], v[148:149]
	v_pk_fma_f32 v[32:33], v[146:147], v[32:33], v[150:151]
	s_nop 0
	v_cndmask_b32_e64 v35, v33, v209, s[84:85]
	v_cndmask_b32_e64 v34, v32, v209, s[84:85]
	v_cndmask_b32_e64 v33, v39, v209, s[84:85]
	v_cndmask_b32_e64 v32, v38, v209, s[84:85]
	s_nop 1
	v_cndmask_b32_dpp v234, v32, v226, vcc quad_perm:[1,0,3,2] row_mask:0xf bank_mask:0xf
	v_cndmask_b32_dpp v235, v33, v227, vcc quad_perm:[1,0,3,2] row_mask:0xf bank_mask:0xf
	v_cndmask_b32_dpp v236, v34, v228, vcc quad_perm:[1,0,3,2] row_mask:0xf bank_mask:0xf
	v_cndmask_b32_dpp v237, v35, v229, vcc quad_perm:[1,0,3,2] row_mask:0xf bank_mask:0xf
	s_not_b64 vcc, vcc
	s_nop 0
	v_cndmask_b32_dpp v32, v226, v32, vcc quad_perm:[1,0,3,2] row_mask:0xf bank_mask:0xf
	v_cndmask_b32_dpp v33, v227, v33, vcc quad_perm:[1,0,3,2] row_mask:0xf bank_mask:0xf
	v_cndmask_b32_dpp v34, v228, v34, vcc quad_perm:[1,0,3,2] row_mask:0xf bank_mask:0xf
	v_cndmask_b32_dpp v35, v229, v35, vcc quad_perm:[1,0,3,2] row_mask:0xf bank_mask:0xf
	s_not_b64 vcc, vcc
	v_lshl_add_u64 v[242:243], v[36:37], 0, v[238:239]
	v_lshl_add_u64 v[244:245], v[36:37], 0, v[240:241]
	global_store_dwordx4 v[242:243], v[234:237], off
	global_store_dwordx4 v[244:245], v[32:35], off
	s_nop 1
	v_sub_f32_e32 v33, v107, v218
	v_sub_f32_e32 v32, v106, v218
	v_sub_f32_e32 v35, v105, v218
	v_sub_f32_e32 v34, v104, v218
	v_pk_mul_f32 v[34:35], v[218:219], v[34:35] op_sel:[1,0]
	v_pk_mul_f32 v[32:33], v[218:219], v[32:33] op_sel:[1,0]
	v_pk_fma_f32 v[38:39], v[140:141], v[34:35], v[136:137]
	v_pk_fma_f32 v[32:33], v[142:143], v[32:33], v[138:139]
	s_nop 0
	v_cndmask_b32_e64 v35, v33, v209, s[84:85]
	v_cndmask_b32_e64 v34, v32, v209, s[84:85]
	v_cndmask_b32_e64 v33, v39, v209, s[84:85]
	v_cndmask_b32_e64 v32, v38, v209, s[84:85]
	v_mov_b32_e32 v230, v32
	v_mov_b32_e32 v231, v33
	v_mov_b32_e32 v232, v34
	v_mov_b32_e32 v233, v35
	s_nop 1
	v_sub_f32_e32 v33, v87, v218
	v_sub_f32_e32 v32, v86, v218
	v_sub_f32_e32 v35, v85, v218
	v_sub_f32_e32 v34, v84, v218
	v_pk_mul_f32 v[34:35], v[218:219], v[34:35] op_sel:[1,0]
	v_pk_mul_f32 v[32:33], v[218:219], v[32:33] op_sel:[1,0]
	v_pk_fma_f32 v[38:39], v[128:129], v[34:35], v[132:133]
	v_pk_fma_f32 v[32:33], v[130:131], v[32:33], v[134:135]
	s_nop 0
	v_cndmask_b32_e64 v35, v33, v209, s[84:85]
	v_cndmask_b32_e64 v34, v32, v209, s[84:85]
	v_cndmask_b32_e64 v33, v39, v209, s[84:85]
	v_cndmask_b32_e64 v32, v38, v209, s[84:85]
	s_nop 1
	v_cndmask_b32_dpp v234, v32, v230, vcc quad_perm:[1,0,3,2] row_mask:0xf bank_mask:0xf
	v_cndmask_b32_dpp v235, v33, v231, vcc quad_perm:[1,0,3,2] row_mask:0xf bank_mask:0xf
	v_cndmask_b32_dpp v236, v34, v232, vcc quad_perm:[1,0,3,2] row_mask:0xf bank_mask:0xf
	v_cndmask_b32_dpp v237, v35, v233, vcc quad_perm:[1,0,3,2] row_mask:0xf bank_mask:0xf
	s_not_b64 vcc, vcc
	s_nop 0
	v_cndmask_b32_dpp v32, v230, v32, vcc quad_perm:[1,0,3,2] row_mask:0xf bank_mask:0xf
	v_cndmask_b32_dpp v33, v231, v33, vcc quad_perm:[1,0,3,2] row_mask:0xf bank_mask:0xf
	v_cndmask_b32_dpp v34, v232, v34, vcc quad_perm:[1,0,3,2] row_mask:0xf bank_mask:0xf
	v_cndmask_b32_dpp v35, v233, v35, vcc quad_perm:[1,0,3,2] row_mask:0xf bank_mask:0xf
	s_not_b64 vcc, vcc
	v_lshl_add_u64 v[242:243], v[36:37], 0, v[238:239]
	v_lshl_add_u64 v[244:245], v[36:37], 0, v[240:241]
	global_store_dwordx4 v[242:243], v[234:237], off offset:512
	global_store_dwordx4 v[244:245], v[32:35], off offset:512
	ds_read_b64 v[32:33], v196
	v_add_u32_e32 v36, s39, v187
	v_ashrrev_i32_e32 v37, 31, v36
	v_lshlrev_b64 v[36:37], 12, v[36:37]
	ds_read_b64 v[34:35], v197
	ds_read_b64 v[38:39], v198
	ds_read_b64 v[40:41], v199
	s_waitcnt lgkmcnt(3)
	v_sub_f32_e32 v7, v7, v32
	v_sub_f32_e32 v6, v6, v32
	v_sub_f32_e32 v5, v5, v32
	v_sub_f32_e32 v4, v4, v32
	v_pk_mul_f32 v[4:5], v[32:33], v[4:5] op_sel:[1,0]
	v_pk_mul_f32 v[6:7], v[32:33], v[6:7] op_sel:[1,0]
	v_sub_f32_e32 v3, v3, v32
	v_sub_f32_e32 v2, v2, v32
	v_sub_f32_e32 v1, v1, v32
	v_sub_f32_e32 v0, v0, v32
	v_lshl_add_u64 v[36:37], s[58:59], 0, v[36:37]
	v_pk_fma_f32 v[6:7], v[142:143], v[6:7], v[138:139]
	v_pk_fma_f32 v[4:5], v[140:141], v[4:5], v[136:137]
	v_pk_mul_f32 v[0:1], v[32:33], v[0:1] op_sel:[1,0]
	v_pk_mul_f32 v[2:3], v[32:33], v[2:3] op_sel:[1,0]
	v_lshl_add_u64 v[36:37], v[36:37], 0, v[178:179]
	v_cndmask_b32_e64 v7, v7, v209, s[84:85]
	v_cndmask_b32_e64 v6, v6, v209, s[84:85]
	v_cndmask_b32_e64 v5, v5, v209, s[84:85]
	v_cndmask_b32_e64 v4, v4, v209, s[84:85]
	v_pk_fma_f32 v[2:3], v[130:131], v[2:3], v[134:135]
	v_pk_fma_f32 v[0:1], v[128:129], v[0:1], v[132:133]
	v_mov_b32_e32 v226, v4
	v_mov_b32_e32 v227, v5
	v_mov_b32_e32 v228, v6
	v_mov_b32_e32 v229, v7
	v_cndmask_b32_e64 v3, v3, v209, s[84:85]
	v_cndmask_b32_e64 v2, v2, v209, s[84:85]
	v_cndmask_b32_e64 v1, v1, v209, s[84:85]
	v_cndmask_b32_e64 v0, v0, v209, s[84:85]
	v_add_u32_e32 v4, s39, v188
	s_nop 1
	v_cndmask_b32_dpp v234, v0, v226, vcc quad_perm:[1,0,3,2] row_mask:0xf bank_mask:0xf
	v_cndmask_b32_dpp v235, v1, v227, vcc quad_perm:[1,0,3,2] row_mask:0xf bank_mask:0xf
	v_cndmask_b32_dpp v236, v2, v228, vcc quad_perm:[1,0,3,2] row_mask:0xf bank_mask:0xf
	v_cndmask_b32_dpp v237, v3, v229, vcc quad_perm:[1,0,3,2] row_mask:0xf bank_mask:0xf
	s_not_b64 vcc, vcc
	s_nop 0
	v_cndmask_b32_dpp v0, v226, v0, vcc quad_perm:[1,0,3,2] row_mask:0xf bank_mask:0xf
	v_cndmask_b32_dpp v1, v227, v1, vcc quad_perm:[1,0,3,2] row_mask:0xf bank_mask:0xf
	v_cndmask_b32_dpp v2, v228, v2, vcc quad_perm:[1,0,3,2] row_mask:0xf bank_mask:0xf
	v_cndmask_b32_dpp v3, v229, v3, vcc quad_perm:[1,0,3,2] row_mask:0xf bank_mask:0xf
	s_not_b64 vcc, vcc
	v_lshl_add_u64 v[242:243], v[36:37], 0, v[238:239]
	v_lshl_add_u64 v[244:245], v[36:37], 0, v[240:241]
	global_store_dwordx4 v[242:243], v[234:237], off offset:512
	global_store_dwordx4 v[244:245], v[0:3], off offset:512
	v_ashrrev_i32_e32 v5, 31, v4
	v_lshlrev_b64 v[4:5], 12, v[4:5]
	s_waitcnt lgkmcnt(2)
	v_sub_f32_e32 v1, v31, v34
	v_sub_f32_e32 v0, v30, v34
	v_sub_f32_e32 v3, v29, v34
	v_sub_f32_e32 v2, v28, v34
	v_pk_mul_f32 v[2:3], v[34:35], v[2:3] op_sel:[1,0]
	v_pk_mul_f32 v[0:1], v[34:35], v[0:1] op_sel:[1,0]
	v_pk_fma_f32 v[6:7], v[156:157], v[2:3], v[152:153]
	v_pk_fma_f32 v[0:1], v[158:159], v[0:1], v[154:155]
	v_lshl_add_u64 v[4:5], s[58:59], 0, v[4:5]
	v_cndmask_b32_e64 v3, v1, v209, s[84:85]
	v_cndmask_b32_e64 v2, v0, v209, s[84:85]
	v_cndmask_b32_e64 v1, v7, v209, s[84:85]
	v_cndmask_b32_e64 v0, v6, v209, s[84:85]
	v_lshl_add_u64 v[4:5], v[4:5], 0, v[178:179]
	v_mov_b32_e32 v230, v0
	v_mov_b32_e32 v231, v1
	v_mov_b32_e32 v232, v2
	v_mov_b32_e32 v233, v3
	v_sub_f32_e32 v15, v15, v32
	v_sub_f32_e32 v14, v14, v32
	v_sub_f32_e32 v1, v27, v34
	v_sub_f32_e32 v0, v26, v34
	v_sub_f32_e32 v3, v25, v34
	v_sub_f32_e32 v2, v24, v34
	v_pk_mul_f32 v[2:3], v[34:35], v[2:3] op_sel:[1,0]
	v_pk_mul_f32 v[0:1], v[34:35], v[0:1] op_sel:[1,0]
	v_pk_fma_f32 v[6:7], v[144:145], v[2:3], v[148:149]
	v_pk_fma_f32 v[0:1], v[146:147], v[0:1], v[150:151]
	v_sub_f32_e32 v13, v13, v32
	v_cndmask_b32_e64 v3, v1, v209, s[84:85]
	v_cndmask_b32_e64 v2, v0, v209, s[84:85]
	v_cndmask_b32_e64 v1, v7, v209, s[84:85]
	v_cndmask_b32_e64 v0, v6, v209, s[84:85]
	s_nop 1
	v_cndmask_b32_dpp v234, v0, v230, vcc quad_perm:[1,0,3,2] row_mask:0xf bank_mask:0xf
	v_cndmask_b32_dpp v235, v1, v231, vcc quad_perm:[1,0,3,2] row_mask:0xf bank_mask:0xf
	v_cndmask_b32_dpp v236, v2, v232, vcc quad_perm:[1,0,3,2] row_mask:0xf bank_mask:0xf
	v_cndmask_b32_dpp v237, v3, v233, vcc quad_perm:[1,0,3,2] row_mask:0xf bank_mask:0xf
	s_not_b64 vcc, vcc
	s_nop 0
	v_cndmask_b32_dpp v0, v230, v0, vcc quad_perm:[1,0,3,2] row_mask:0xf bank_mask:0xf
	v_cndmask_b32_dpp v1, v231, v1, vcc quad_perm:[1,0,3,2] row_mask:0xf bank_mask:0xf
	v_cndmask_b32_dpp v2, v232, v2, vcc quad_perm:[1,0,3,2] row_mask:0xf bank_mask:0xf
	v_cndmask_b32_dpp v3, v233, v3, vcc quad_perm:[1,0,3,2] row_mask:0xf bank_mask:0xf
	s_not_b64 vcc, vcc
	v_lshl_add_u64 v[242:243], v[4:5], 0, v[238:239]
	v_lshl_add_u64 v[244:245], v[4:5], 0, v[240:241]
	global_store_dwordx4 v[242:243], v[234:237], off
	global_store_dwordx4 v[244:245], v[0:3], off
	v_sub_f32_e32 v12, v12, v32
	v_sub_f32_e32 v11, v11, v32
	v_sub_f32_e32 v1, v23, v34
	v_sub_f32_e32 v0, v22, v34
	v_sub_f32_e32 v3, v21, v34
	v_sub_f32_e32 v2, v20, v34
	v_pk_mul_f32 v[2:3], v[34:35], v[2:3] op_sel:[1,0]
	v_pk_mul_f32 v[0:1], v[34:35], v[0:1] op_sel:[1,0]
	v_pk_fma_f32 v[6:7], v[140:141], v[2:3], v[136:137]
	v_pk_fma_f32 v[0:1], v[142:143], v[0:1], v[138:139]
	v_sub_f32_e32 v10, v10, v32
	v_cndmask_b32_e64 v3, v1, v209, s[84:85]
	v_cndmask_b32_e64 v2, v0, v209, s[84:85]
	v_cndmask_b32_e64 v1, v7, v209, s[84:85]
	v_cndmask_b32_e64 v0, v6, v209, s[84:85]
	v_mov_b32_e32 v226, v0
	v_mov_b32_e32 v227, v1
	v_mov_b32_e32 v228, v2
	v_mov_b32_e32 v229, v3
	v_sub_f32_e32 v9, v9, v32
	v_sub_f32_e32 v8, v8, v32
	v_sub_f32_e32 v1, v19, v34
	v_sub_f32_e32 v0, v18, v34
	v_sub_f32_e32 v3, v17, v34
	v_sub_f32_e32 v2, v16, v34
	v_pk_mul_f32 v[2:3], v[34:35], v[2:3] op_sel:[1,0]
	v_pk_mul_f32 v[0:1], v[34:35], v[0:1] op_sel:[1,0]
	v_pk_fma_f32 v[6:7], v[128:129], v[2:3], v[132:133]
	v_pk_fma_f32 v[0:1], v[130:131], v[0:1], v[134:135]
	v_pk_mul_f32 v[12:13], v[32:33], v[12:13] op_sel:[1,0]
	v_cndmask_b32_e64 v3, v1, v209, s[84:85]
	v_cndmask_b32_e64 v2, v0, v209, s[84:85]
	v_cndmask_b32_e64 v1, v7, v209, s[84:85]
	v_cndmask_b32_e64 v0, v6, v209, s[84:85]
	s_nop 1
	v_cndmask_b32_dpp v234, v0, v226, vcc quad_perm:[1,0,3,2] row_mask:0xf bank_mask:0xf
	v_cndmask_b32_dpp v235, v1, v227, vcc quad_perm:[1,0,3,2] row_mask:0xf bank_mask:0xf
	v_cndmask_b32_dpp v236, v2, v228, vcc quad_perm:[1,0,3,2] row_mask:0xf bank_mask:0xf
	v_cndmask_b32_dpp v237, v3, v229, vcc quad_perm:[1,0,3,2] row_mask:0xf bank_mask:0xf
	s_not_b64 vcc, vcc
	s_nop 0
	v_cndmask_b32_dpp v0, v226, v0, vcc quad_perm:[1,0,3,2] row_mask:0xf bank_mask:0xf
	v_cndmask_b32_dpp v1, v227, v1, vcc quad_perm:[1,0,3,2] row_mask:0xf bank_mask:0xf
	v_cndmask_b32_dpp v2, v228, v2, vcc quad_perm:[1,0,3,2] row_mask:0xf bank_mask:0xf
	v_cndmask_b32_dpp v3, v229, v3, vcc quad_perm:[1,0,3,2] row_mask:0xf bank_mask:0xf
	s_not_b64 vcc, vcc
	v_lshl_add_u64 v[242:243], v[4:5], 0, v[238:239]
	v_lshl_add_u64 v[244:245], v[4:5], 0, v[240:241]
	global_store_dwordx4 v[242:243], v[234:237], off offset:512
	global_store_dwordx4 v[244:245], v[0:3], off offset:512
	v_add_u32_e32 v4, s39, v189
	v_ashrrev_i32_e32 v5, 31, v4
	s_waitcnt lgkmcnt(1)
	v_sub_f32_e32 v1, v95, v38
	v_sub_f32_e32 v0, v94, v38
	v_sub_f32_e32 v3, v93, v38
	v_sub_f32_e32 v2, v92, v38
	v_pk_mul_f32 v[2:3], v[38:39], v[2:3] op_sel:[1,0]
	v_pk_mul_f32 v[0:1], v[38:39], v[0:1] op_sel:[1,0]
	v_lshlrev_b64 v[4:5], 12, v[4:5]
	v_pk_fma_f32 v[0:1], v[158:159], v[0:1], v[154:155]
	v_pk_fma_f32 v[6:7], v[156:157], v[2:3], v[152:153]
	v_lshl_add_u64 v[4:5], s[58:59], 0, v[4:5]
	v_cndmask_b32_e64 v3, v1, v209, s[84:85]
	v_cndmask_b32_e64 v2, v0, v209, s[84:85]
	v_cndmask_b32_e64 v1, v7, v209, s[84:85]
	v_cndmask_b32_e64 v0, v6, v209, s[84:85]
	v_lshl_add_u64 v[4:5], v[4:5], 0, v[178:179]
	v_mov_b32_e32 v230, v0
	v_mov_b32_e32 v231, v1
	v_mov_b32_e32 v232, v2
	v_mov_b32_e32 v233, v3
	v_pk_mul_f32 v[14:15], v[32:33], v[14:15] op_sel:[1,0]
	v_pk_mul_f32 v[8:9], v[32:33], v[8:9] op_sel:[1,0]
	v_sub_f32_e32 v1, v75, v38
	v_sub_f32_e32 v0, v74, v38
	v_sub_f32_e32 v3, v73, v38
	v_sub_f32_e32 v2, v72, v38
	v_pk_mul_f32 v[2:3], v[38:39], v[2:3] op_sel:[1,0]
	v_pk_mul_f32 v[0:1], v[38:39], v[0:1] op_sel:[1,0]
	v_pk_fma_f32 v[6:7], v[144:145], v[2:3], v[148:149]
	v_pk_fma_f32 v[0:1], v[146:147], v[0:1], v[150:151]
	v_pk_mul_f32 v[10:11], v[32:33], v[10:11] op_sel:[1,0]
	v_cndmask_b32_e64 v3, v1, v209, s[84:85]
	v_cndmask_b32_e64 v2, v0, v209, s[84:85]
	v_cndmask_b32_e64 v1, v7, v209, s[84:85]
	v_cndmask_b32_e64 v0, v6, v209, s[84:85]
	s_nop 1
	v_cndmask_b32_dpp v234, v0, v230, vcc quad_perm:[1,0,3,2] row_mask:0xf bank_mask:0xf
	v_cndmask_b32_dpp v235, v1, v231, vcc quad_perm:[1,0,3,2] row_mask:0xf bank_mask:0xf
	v_cndmask_b32_dpp v236, v2, v232, vcc quad_perm:[1,0,3,2] row_mask:0xf bank_mask:0xf
	v_cndmask_b32_dpp v237, v3, v233, vcc quad_perm:[1,0,3,2] row_mask:0xf bank_mask:0xf
	s_not_b64 vcc, vcc
	s_nop 0
	v_cndmask_b32_dpp v0, v230, v0, vcc quad_perm:[1,0,3,2] row_mask:0xf bank_mask:0xf
	v_cndmask_b32_dpp v1, v231, v1, vcc quad_perm:[1,0,3,2] row_mask:0xf bank_mask:0xf
	v_cndmask_b32_dpp v2, v232, v2, vcc quad_perm:[1,0,3,2] row_mask:0xf bank_mask:0xf
	v_cndmask_b32_dpp v3, v233, v3, vcc quad_perm:[1,0,3,2] row_mask:0xf bank_mask:0xf
	s_not_b64 vcc, vcc
	v_lshl_add_u64 v[242:243], v[4:5], 0, v[238:239]
	v_lshl_add_u64 v[244:245], v[4:5], 0, v[240:241]
	global_store_dwordx4 v[242:243], v[234:237], off
	global_store_dwordx4 v[244:245], v[0:3], off
	v_pk_fma_f32 v[14:15], v[158:159], v[14:15], v[154:155]
	v_pk_fma_f32 v[12:13], v[156:157], v[12:13], v[152:153]
	v_sub_f32_e32 v1, v67, v38
	v_sub_f32_e32 v0, v66, v38
	v_sub_f32_e32 v3, v65, v38
	v_sub_f32_e32 v2, v64, v38
	v_pk_mul_f32 v[2:3], v[38:39], v[2:3] op_sel:[1,0]
	v_pk_mul_f32 v[0:1], v[38:39], v[0:1] op_sel:[1,0]
	v_pk_fma_f32 v[6:7], v[140:141], v[2:3], v[136:137]
	v_pk_fma_f32 v[0:1], v[142:143], v[0:1], v[138:139]
	v_pk_fma_f32 v[10:11], v[146:147], v[10:11], v[150:151]
	v_cndmask_b32_e64 v3, v1, v209, s[84:85]
	v_cndmask_b32_e64 v2, v0, v209, s[84:85]
	v_cndmask_b32_e64 v1, v7, v209, s[84:85]
	v_cndmask_b32_e64 v0, v6, v209, s[84:85]
	v_mov_b32_e32 v226, v0
	v_mov_b32_e32 v227, v1
	v_mov_b32_e32 v228, v2
	v_mov_b32_e32 v229, v3
	v_pk_fma_f32 v[8:9], v[144:145], v[8:9], v[148:149]
	v_cndmask_b32_e64 v15, v15, v209, s[84:85]
	v_sub_f32_e32 v1, v63, v38
	v_sub_f32_e32 v0, v62, v38
	v_sub_f32_e32 v3, v61, v38
	v_sub_f32_e32 v2, v60, v38
	v_pk_mul_f32 v[2:3], v[38:39], v[2:3] op_sel:[1,0]
	v_pk_mul_f32 v[0:1], v[38:39], v[0:1] op_sel:[1,0]
	v_pk_fma_f32 v[6:7], v[128:129], v[2:3], v[132:133]
	v_pk_fma_f32 v[0:1], v[130:131], v[0:1], v[134:135]
	v_cndmask_b32_e64 v14, v14, v209, s[84:85]
	v_cndmask_b32_e64 v3, v1, v209, s[84:85]
	v_cndmask_b32_e64 v2, v0, v209, s[84:85]
	v_cndmask_b32_e64 v1, v7, v209, s[84:85]
	v_cndmask_b32_e64 v0, v6, v209, s[84:85]
	s_nop 1
	v_cndmask_b32_dpp v234, v0, v226, vcc quad_perm:[1,0,3,2] row_mask:0xf bank_mask:0xf
	v_cndmask_b32_dpp v235, v1, v227, vcc quad_perm:[1,0,3,2] row_mask:0xf bank_mask:0xf
	v_cndmask_b32_dpp v236, v2, v228, vcc quad_perm:[1,0,3,2] row_mask:0xf bank_mask:0xf
	v_cndmask_b32_dpp v237, v3, v229, vcc quad_perm:[1,0,3,2] row_mask:0xf bank_mask:0xf
	s_not_b64 vcc, vcc
	s_nop 0
	v_cndmask_b32_dpp v0, v226, v0, vcc quad_perm:[1,0,3,2] row_mask:0xf bank_mask:0xf
	v_cndmask_b32_dpp v1, v227, v1, vcc quad_perm:[1,0,3,2] row_mask:0xf bank_mask:0xf
	v_cndmask_b32_dpp v2, v228, v2, vcc quad_perm:[1,0,3,2] row_mask:0xf bank_mask:0xf
	v_cndmask_b32_dpp v3, v229, v3, vcc quad_perm:[1,0,3,2] row_mask:0xf bank_mask:0xf
	s_not_b64 vcc, vcc
	v_lshl_add_u64 v[242:243], v[4:5], 0, v[238:239]
	v_lshl_add_u64 v[244:245], v[4:5], 0, v[240:241]
	global_store_dwordx4 v[242:243], v[234:237], off offset:512
	global_store_dwordx4 v[244:245], v[0:3], off offset:512
	v_add_u32_e32 v4, s39, v190
	v_ashrrev_i32_e32 v5, 31, v4
	s_waitcnt lgkmcnt(0)
	v_sub_f32_e32 v1, v127, v40
	v_sub_f32_e32 v0, v126, v40
	v_sub_f32_e32 v3, v125, v40
	v_sub_f32_e32 v2, v124, v40
	v_pk_mul_f32 v[2:3], v[40:41], v[2:3] op_sel:[1,0]
	v_pk_mul_f32 v[0:1], v[40:41], v[0:1] op_sel:[1,0]
	v_lshlrev_b64 v[4:5], 12, v[4:5]
	v_pk_fma_f32 v[0:1], v[158:159], v[0:1], v[154:155]
	v_pk_fma_f32 v[6:7], v[156:157], v[2:3], v[152:153]
	v_lshl_add_u64 v[4:5], s[58:59], 0, v[4:5]
	v_cndmask_b32_e64 v3, v1, v209, s[84:85]
	v_cndmask_b32_e64 v2, v0, v209, s[84:85]
	v_cndmask_b32_e64 v1, v7, v209, s[84:85]
	v_cndmask_b32_e64 v0, v6, v209, s[84:85]
	v_lshl_add_u64 v[4:5], v[4:5], 0, v[178:179]
	v_mov_b32_e32 v230, v0
	v_mov_b32_e32 v231, v1
	v_mov_b32_e32 v232, v2
	v_mov_b32_e32 v233, v3
	v_cndmask_b32_e64 v13, v13, v209, s[84:85]
	v_cndmask_b32_e64 v12, v12, v209, s[84:85]
	v_sub_f32_e32 v1, v119, v40
	v_sub_f32_e32 v0, v118, v40
	v_sub_f32_e32 v3, v117, v40
	v_sub_f32_e32 v2, v116, v40
	v_pk_mul_f32 v[2:3], v[40:41], v[2:3] op_sel:[1,0]
	v_pk_mul_f32 v[0:1], v[40:41], v[0:1] op_sel:[1,0]
	v_pk_fma_f32 v[6:7], v[144:145], v[2:3], v[148:149]
	v_pk_fma_f32 v[0:1], v[146:147], v[0:1], v[150:151]
	v_cndmask_b32_e64 v11, v11, v209, s[84:85]
	v_cndmask_b32_e64 v3, v1, v209, s[84:85]
	v_cndmask_b32_e64 v2, v0, v209, s[84:85]
	v_cndmask_b32_e64 v1, v7, v209, s[84:85]
	v_cndmask_b32_e64 v0, v6, v209, s[84:85]
	s_nop 1
	v_cndmask_b32_dpp v234, v0, v230, vcc quad_perm:[1,0,3,2] row_mask:0xf bank_mask:0xf
	v_cndmask_b32_dpp v235, v1, v231, vcc quad_perm:[1,0,3,2] row_mask:0xf bank_mask:0xf
	v_cndmask_b32_dpp v236, v2, v232, vcc quad_perm:[1,0,3,2] row_mask:0xf bank_mask:0xf
	v_cndmask_b32_dpp v237, v3, v233, vcc quad_perm:[1,0,3,2] row_mask:0xf bank_mask:0xf
	s_not_b64 vcc, vcc
	s_nop 0
	v_cndmask_b32_dpp v0, v230, v0, vcc quad_perm:[1,0,3,2] row_mask:0xf bank_mask:0xf
	v_cndmask_b32_dpp v1, v231, v1, vcc quad_perm:[1,0,3,2] row_mask:0xf bank_mask:0xf
	v_cndmask_b32_dpp v2, v232, v2, vcc quad_perm:[1,0,3,2] row_mask:0xf bank_mask:0xf
	v_cndmask_b32_dpp v3, v233, v3, vcc quad_perm:[1,0,3,2] row_mask:0xf bank_mask:0xf
	s_not_b64 vcc, vcc
	v_lshl_add_u64 v[242:243], v[4:5], 0, v[238:239]
	v_lshl_add_u64 v[244:245], v[4:5], 0, v[240:241]
	global_store_dwordx4 v[242:243], v[234:237], off
	global_store_dwordx4 v[244:245], v[0:3], off
	v_cndmask_b32_e64 v10, v10, v209, s[84:85]
	v_cndmask_b32_e64 v9, v9, v209, s[84:85]
	v_sub_f32_e32 v1, v111, v40
	v_sub_f32_e32 v0, v110, v40
	v_sub_f32_e32 v3, v109, v40
	v_sub_f32_e32 v2, v108, v40
	v_pk_mul_f32 v[2:3], v[40:41], v[2:3] op_sel:[1,0]
	v_pk_mul_f32 v[0:1], v[40:41], v[0:1] op_sel:[1,0]
	v_pk_fma_f32 v[6:7], v[140:141], v[2:3], v[136:137]
	v_pk_fma_f32 v[0:1], v[142:143], v[0:1], v[138:139]
	v_cndmask_b32_e64 v8, v8, v209, s[84:85]
	v_cndmask_b32_e64 v3, v1, v209, s[84:85]
	v_cndmask_b32_e64 v2, v0, v209, s[84:85]
	v_cndmask_b32_e64 v1, v7, v209, s[84:85]
	v_cndmask_b32_e64 v0, v6, v209, s[84:85]
	v_mov_b32_e32 v226, v0
	v_mov_b32_e32 v227, v1
	v_mov_b32_e32 v228, v2
	v_mov_b32_e32 v229, v3
	v_mov_b32_e32 v230, v12
	v_mov_b32_e32 v231, v13
	v_mov_b32_e32 v232, v14
	v_mov_b32_e32 v233, v15
	s_nop 1
	v_cndmask_b32_dpp v234, v8, v230, vcc quad_perm:[1,0,3,2] row_mask:0xf bank_mask:0xf
	v_cndmask_b32_dpp v235, v9, v231, vcc quad_perm:[1,0,3,2] row_mask:0xf bank_mask:0xf
	v_cndmask_b32_dpp v236, v10, v232, vcc quad_perm:[1,0,3,2] row_mask:0xf bank_mask:0xf
	v_cndmask_b32_dpp v237, v11, v233, vcc quad_perm:[1,0,3,2] row_mask:0xf bank_mask:0xf
	s_not_b64 vcc, vcc
	s_nop 0
	v_cndmask_b32_dpp v8, v230, v8, vcc quad_perm:[1,0,3,2] row_mask:0xf bank_mask:0xf
	v_cndmask_b32_dpp v9, v231, v9, vcc quad_perm:[1,0,3,2] row_mask:0xf bank_mask:0xf
	v_cndmask_b32_dpp v10, v232, v10, vcc quad_perm:[1,0,3,2] row_mask:0xf bank_mask:0xf
	v_cndmask_b32_dpp v11, v233, v11, vcc quad_perm:[1,0,3,2] row_mask:0xf bank_mask:0xf
	s_not_b64 vcc, vcc
	v_lshl_add_u64 v[242:243], v[36:37], 0, v[238:239]
	v_lshl_add_u64 v[244:245], v[36:37], 0, v[240:241]
	global_store_dwordx4 v[242:243], v[234:237], off
	global_store_dwordx4 v[244:245], v[8:11], off
	v_sub_f32_e32 v1, v103, v40
	v_sub_f32_e32 v0, v102, v40
	v_sub_f32_e32 v3, v101, v40
	v_sub_f32_e32 v2, v100, v40
	v_pk_mul_f32 v[2:3], v[40:41], v[2:3] op_sel:[1,0]
	v_pk_mul_f32 v[0:1], v[40:41], v[0:1] op_sel:[1,0]
	v_pk_fma_f32 v[6:7], v[128:129], v[2:3], v[132:133]
	v_pk_fma_f32 v[0:1], v[130:131], v[0:1], v[134:135]
	s_nop 0
	v_cndmask_b32_e64 v3, v1, v209, s[84:85]
	v_cndmask_b32_e64 v2, v0, v209, s[84:85]
	v_cndmask_b32_e64 v1, v7, v209, s[84:85]
	v_cndmask_b32_e64 v0, v6, v209, s[84:85]
	s_nop 1
	v_cndmask_b32_dpp v234, v0, v226, vcc quad_perm:[1,0,3,2] row_mask:0xf bank_mask:0xf
	v_cndmask_b32_dpp v235, v1, v227, vcc quad_perm:[1,0,3,2] row_mask:0xf bank_mask:0xf
	v_cndmask_b32_dpp v236, v2, v228, vcc quad_perm:[1,0,3,2] row_mask:0xf bank_mask:0xf
	v_cndmask_b32_dpp v237, v3, v229, vcc quad_perm:[1,0,3,2] row_mask:0xf bank_mask:0xf
	s_not_b64 vcc, vcc
	s_nop 0
	v_cndmask_b32_dpp v0, v226, v0, vcc quad_perm:[1,0,3,2] row_mask:0xf bank_mask:0xf
	v_cndmask_b32_dpp v1, v227, v1, vcc quad_perm:[1,0,3,2] row_mask:0xf bank_mask:0xf
	v_cndmask_b32_dpp v2, v228, v2, vcc quad_perm:[1,0,3,2] row_mask:0xf bank_mask:0xf
	v_cndmask_b32_dpp v3, v229, v3, vcc quad_perm:[1,0,3,2] row_mask:0xf bank_mask:0xf
	s_not_b64 vcc, vcc
	v_lshl_add_u64 v[242:243], v[4:5], 0, v[238:239]
	v_lshl_add_u64 v[244:245], v[4:5], 0, v[240:241]
	global_store_dwordx4 v[242:243], v[234:237], off offset:512
	global_store_dwordx4 v[244:245], v[0:3], off offset:512
	s_waitcnt lgkmcnt(0)
	s_barrier
	s_andn2_b64 vcc, exec, s[10:11]
	s_mov_b64 s[10:11], -1
	s_cbranch_vccnz .LBB0_380
	s_andn2_b64 vcc, exec, s[22:23]
	s_cbranch_vccnz .LBB0_379
	s_barrier
	s_branch .LBB0_379
